# rotK tab3 + P0 row loop prefetching two rows ahead (two alternating next-row buffers, one counted vmcnt(9) at the loop bottom instead of a full drain)
# baseline (speedup 1.0000x reference)
; __device__ __forceinline__ void phase0(const Params& P, LAS unsigned char* lds, int tid, int lane, int wave) {
;     ...
;     f32x4 g4[4];
; #pragma unroll
;     for (int j = 0; j < 4; ++j) g4[j] = *(const f32x4*)(P.gain + 4 * lane + 256 * j);
;     const float bfv = P.bfg[lane & 7];
;     f32x4 nv[4];
;     if (gw < MT) {
;         const float* xrow = (gw < MP) ? P.xp + (size_t)gw * 1024 : P.xs + (size_t)(gw - MP) * 1024;
; #pragma unroll
;         for (int j = 0; j < 4; ++j) nv[j] = *(const f32x4*)(xrow + 4 * lane + 256 * j);
;     }
;     for (int m = gw; m < MT; m += NGW) {
;         f32x4 v[4]; float ss = 0.f;
; #pragma unroll
;         for (int j = 0; j < 4; ++j) { v[j] = nv[j]; ss += (v[j][0] * v[j][0] + v[j][1] * v[j][1]) + (v[j][2] * v[j][2] + v[j][3] * v[j][3]); }
;         if (m + NGW < MT) {
;             const int mn = m + NGW;
;             const float* xrow = (mn < MP) ? P.xp + (size_t)mn * 1024 : P.xs + (size_t)(mn - MP) * 1024;
; #pragma unroll
;             for (int j = 0; j < 4; ++j) nv[j] = *(const f32x4*)(xrow + 4 * lane + 256 * j);
;         }
.LBB0_28:
	v_readlane_b32 s0, v241, 10
	v_readlane_b32 s1, v241, 11
	s_cmp_lt_i32 s0, 0x10100
	s_cselect_b64 s[0:1], -1, 0
	v_writelane_b32 v241, s0, 12
	s_mov_b64 s[6:7], s[38:39]
	s_mov_b64 s[8:9], s[40:41]
	v_writelane_b32 v241, s1, 13
	v_writelane_b32 v241, s4, 14
	s_and_b64 vcc, exec, s[0:1]
	v_mbcnt_lo_u32_b32 v179, -1, 0
	v_writelane_b32 v241, s5, 15
	v_writelane_b32 v241, s6, 16
	v_writelane_b32 v241, s7, 17
	v_writelane_b32 v241, s8, 18
	v_writelane_b32 v241, s9, 19
	v_writelane_b32 v241, s10, 20
	s_waitcnt lgkmcnt(0)
	s_barrier
	v_writelane_b32 v241, s11, 21
	s_cbranch_vccz .LBB0_35
	v_readlane_b32 s24, v241, 10
	v_readlane_b32 s25, v241, 11
	s_add_i32 s3, s24, 0xffff0000
	s_ashr_i32 s25, s24, 31
	s_cmp_lt_i32 s24, 0x10000
	s_cselect_b32 s1, s25, 0
	s_cselect_b32 s0, s24, s3
	s_cselect_b32 s4, s69, s71
	s_cselect_b32 s5, s68, s70
	s_lshl_b64 s[0:1], s[0:1], 12
	s_add_u32 s0, s5, s0
	v_lshlrev_b32_e32 v18, 4, v146
	v_lshlrev_b32_e32 v1, 2, v19
	s_addc_u32 s1, s4, s1
	global_load_dwordx4 v[2:5], v18, s[82:83]
	global_load_dwordx4 v[6:9], v18, s[82:83] offset:1024
	global_load_dwordx4 v[10:13], v18, s[82:83] offset:2048
	global_load_dwordx4 v[14:17], v18, s[82:83] offset:3072
	s_ashr_i32 s85, s84, 31
	global_load_dword v1, v1, s[38:39]
	s_nop 0
	global_load_dwordx4 v[174:177], v18, s[0:1]
	global_load_dwordx4 v[170:173], v18, s[0:1] offset:1024
	global_load_dwordx4 v[166:169], v18, s[0:1] offset:2048
	global_load_dwordx4 v[162:165], v18, s[0:1] offset:3072
	v_mbcnt_hi_u32_b32 v18, -1, v179
	v_and_b32_e32 v19, 64, v18
	v_add_u32_e32 v19, 64, v19
	v_xor_b32_e32 v20, 1, v18
	v_cmp_lt_i32_e32 vcc, v20, v19
	s_lshl_b64 s[18:19], s[24:25], 11
	s_add_u32 s18, s92, s18
	v_cndmask_b32_e32 v20, v18, v20, vcc
	v_lshlrev_b32_e32 v185, 2, v20
	v_xor_b32_e32 v20, 2, v18
	v_cmp_lt_i32_e32 vcc, v20, v19
	v_lshlrev_b32_e32 v26, 2, v146
	v_mov_b32_e32 v29, 0
	v_cndmask_b32_e32 v20, v18, v20, vcc
	v_lshlrev_b32_e32 v186, 2, v20
	v_xor_b32_e32 v20, 4, v18
	v_cmp_lt_i32_e32 vcc, v20, v19
	v_lshlrev_b32_e32 v28, 3, v146
	s_addc_u32 s19, s93, s19
	v_cndmask_b32_e32 v20, v18, v20, vcc
	v_lshlrev_b32_e32 v187, 2, v20
	v_xor_b32_e32 v20, 8, v18
	v_cmp_lt_i32_e32 vcc, v20, v19
	v_lshl_add_u64 v[28:29], s[18:19], 0, v[28:29]
	s_mov_b64 s[18:19], 0x4000000
	v_cndmask_b32_e32 v20, v18, v20, vcc
	v_lshlrev_b32_e32 v188, 2, v20
	v_xor_b32_e32 v20, 16, v18
	v_cmp_lt_i32_e32 vcc, v20, v19
	v_lshlrev_b32_e32 v191, 2, v26
	v_lshl_add_u64 v[180:181], v[28:29], 0, s[18:19]
	v_cndmask_b32_e32 v20, v18, v20, vcc
	v_lshlrev_b32_e32 v189, 2, v20
	v_xor_b32_e32 v20, 32, v18
	v_cmp_lt_i32_e32 vcc, v20, v19
	v_writelane_b32 v241, s24, 10
	s_add_i32 s28, s24, s84
	v_cndmask_b32_e32 v18, v18, v20, vcc
	v_lshlrev_b32_e32 v190, 2, v18
	v_lshl_add_u32 v18, v146, 7, 0
	v_add_u32_e32 v142, 0x11000, v18
	ds_read_b128 v[18:21], v142
	ds_read_b128 v[22:25], v142 offset:16
	ds_read_b128 v[26:29], v142 offset:32
	ds_read_b128 v[30:33], v142 offset:48
	ds_read_b128 v[34:37], v142 offset:64
	ds_read_b128 v[38:41], v142 offset:80
	ds_read_b128 v[42:45], v142 offset:96
	ds_read_b128 v[46:49], v142 offset:112
	ds_read_b128 v[50:53], v142 offset:8192
	ds_read_b128 v[54:57], v142 offset:8208
	ds_read_b128 v[58:61], v142 offset:8224
	ds_read_b128 v[62:65], v142 offset:8240
	ds_read_b128 v[66:69], v142 offset:8256
	ds_read_b128 v[70:73], v142 offset:8272
	ds_read_b128 v[74:77], v142 offset:8288
	ds_read_b128 v[78:81], v142 offset:8304
	ds_read_b128 v[82:85], v142 offset:16384
	ds_read_b128 v[86:89], v142 offset:16400
	ds_read_b128 v[90:93], v142 offset:16416
	ds_read_b128 v[94:97], v142 offset:16432
	ds_read_b128 v[98:101], v142 offset:16448
	ds_read_b128 v[102:105], v142 offset:16464
	ds_read_b128 v[106:109], v142 offset:16480
	ds_read_b128 v[110:113], v142 offset:16496
	ds_read_b128 v[114:117], v142 offset:24576
	ds_read_b128 v[118:121], v142 offset:24592
	ds_read_b128 v[122:125], v142 offset:24608
	ds_read_b128 v[126:129], v142 offset:24624
	ds_read_b128 v[130:133], v142 offset:24640
	ds_read_b128 v[134:137], v142 offset:24656
	ds_read_b128 v[138:141], v142 offset:24672
	ds_read_b128 v[142:145], v142 offset:24688
	v_cmp_gt_u32_e64 s[0:1], 8, v146
	v_cmp_eq_u32_e64 s[4:5], 7, v146
	v_cmp_eq_u32_e64 s[6:7], 6, v146
	v_cmp_eq_u32_e64 s[8:9], 5, v146
	v_cmp_eq_u32_e64 s[10:11], 4, v146
	v_cmp_eq_u32_e64 s[12:13], 3, v146
	v_cmp_eq_u32_e64 s[14:15], 2, v146
	v_cmp_eq_u32_e64 s[16:17], 1, v146
	s_lshl_b64 s[22:23], s[84:85], 11
	v_writelane_b32 v241, s25, 11
	s_ashr_i32 s29, s28, 31
	s_mov_b64 s[24:25], 0
	v_mov_b32_e32 v192, 0x358637bd
	s_mov_b32 s30, 0xf800000
	v_mov_b32_e32 v193, 0x260
	s_mov_b32 s31, 0xbfb8aa3b
	s_mov_b32 s33, 0xb2a5705f
	s_mov_b32 s34, 0x42ce8ed0
	s_mov_b32 s35, 0xc2b17218
	s_mov_b32 s36, 0x7f800000
	s_mov_b32 s37, 0x3f2aaaab
	v_mov_b32_e32 v194, 0x3ecc95a3
	s_mov_b32 s38, 0x3f317218
	s_mov_b32 s39, 0x33800000
	s_mov_b32 s40, 0x24100000
	v_lshlrev_b32_e32 v195, 2, v146
	v_mov_b32_e32 v196, 0x7f800000
	v_mov_b32_e32 v182, 0x3f317218
	s_mov_b32 s45, 0
	s_mov_b32 s50, s28
	s_cmp_lt_i32 s50, 0x10100
	s_cbranch_scc0 .Lp0_nopre
	s_add_i32 s47, s50, 0xffff0000
	s_cmp_lt_i32 s50, 0x10000
	s_cselect_b32 s48, s69, s71
	s_cselect_b32 s49, s68, s70
	s_cselect_b32 s46, s50, s47
	s_lshl_b32 s46, s46, 12
	s_add_u32 s46, s49, s46
	s_addc_u32 s47, s48, 0
	global_load_dwordx4 v[146:149], v191, s[46:47]
	global_load_dwordx4 v[150:153], v191, s[46:47] offset:1024
	global_load_dwordx4 v[154:157], v191, s[46:47] offset:2048
	global_load_dwordx4 v[158:161], v191, s[46:47] offset:3072
	s_waitcnt vmcnt(4)
	s_branch .LBB0_31
; __device__ __forceinline__ void phase0(const Params& P, LAS unsigned char* lds, int tid, int lane, int wave) {
;     ...
;     for (int m = gw; m < MT; m += NGW) {
;         f32x4 v[4]; float ss = 0.f;
; #pragma unroll
;         for (int j = 0; j < 4; ++j) { v[j] = nv[j]; ss += (v[j][0] * v[j][0] + v[j][1] * v[j][1]) + (v[j][2] * v[j][2] + v[j][3] * v[j][3]); }
;         if (m + NGW < MT) {
;             const int mn = m + NGW;
;             const float* xrow = (mn < MP) ? P.xp + (size_t)mn * 1024 : P.xs + (size_t)(mn - MP) * 1024;
; #pragma unroll
;             for (int j = 0; j < 4; ++j) nv[j] = *(const f32x4*)(xrow + 4 * lane + 256 * j);
;         }
.Lp0_nopre:
	s_waitcnt vmcnt(0)
	s_branch .LBB0_31
.LBB0_30:
	s_or_b64 exec, exec, s[18:19]
	s_add_u32 s24, s24, s84
	s_addc_u32 s25, s25, s85
	v_lshl_add_u64 v[180:181], v[180:181], 0, s[22:23]
	s_and_b64 vcc, exec, s[26:27]
	s_mov_b32 s3, s41
	s_cbranch_vccnz .LBB0_35
	s_waitcnt vmcnt(9) lgkmcnt(0)
	s_cmp_eq_u32 s45, 0
	s_cbranch_scc0 .Lp0_cpB
	v_mov_b32_e32 v174, v146
	v_mov_b32_e32 v175, v147
	v_mov_b32_e32 v176, v148
	v_mov_b32_e32 v177, v149
	v_mov_b32_e32 v170, v150
	v_mov_b32_e32 v171, v151
	v_mov_b32_e32 v172, v152
	v_mov_b32_e32 v173, v153
	v_mov_b32_e32 v166, v154
	v_mov_b32_e32 v167, v155
	v_mov_b32_e32 v168, v156
	v_mov_b32_e32 v169, v157
	v_mov_b32_e32 v162, v158
	v_mov_b32_e32 v163, v159
	v_mov_b32_e32 v164, v160
	v_mov_b32_e32 v165, v161
	s_mov_b32 s45, 1
	s_branch .LBB0_31
.Lp0_cpB:
	v_mov_b32_e32 v174, v208
	v_mov_b32_e32 v175, v209
	v_mov_b32_e32 v176, v210
	v_mov_b32_e32 v177, v211
	v_mov_b32_e32 v170, v212
	v_mov_b32_e32 v171, v213
	v_mov_b32_e32 v172, v214
	v_mov_b32_e32 v173, v215
	v_mov_b32_e32 v166, v216
	v_mov_b32_e32 v167, v217
	v_mov_b32_e32 v168, v218
	v_mov_b32_e32 v169, v219
	v_mov_b32_e32 v162, v220
	v_mov_b32_e32 v163, v221
	v_mov_b32_e32 v164, v222
	v_mov_b32_e32 v165, v223
	s_mov_b32 s45, 0
.LBB0_31:
	s_add_i32 s41, s84, s3
	s_add_i32 s18, s41, 0x10000
	s_cmp_gt_i32 s18, 0x100ff
	s_cselect_b64 s[26:27], -1, 0
	s_add_i32 s50, s18, s84
	s_cmp_lt_i32 s50, 0x10100
	s_cbranch_scc0 .LBB0_33
	s_add_i32 s47, s50, 0xffff0000
	s_cmp_lt_i32 s50, 0x10000
	s_cselect_b32 s48, s69, s71
	s_cselect_b32 s49, s68, s70
	s_cselect_b32 s46, s50, s47
	s_lshl_b32 s46, s46, 12
	s_add_u32 s46, s49, s46
	s_addc_u32 s47, s48, 0
	s_cmp_eq_u32 s45, 0
	s_cbranch_scc0 .Lp0_ldB
	global_load_dwordx4 v[208:211], v191, s[46:47]
	global_load_dwordx4 v[212:215], v191, s[46:47] offset:1024
	global_load_dwordx4 v[216:219], v191, s[46:47] offset:2048
	global_load_dwordx4 v[220:223], v191, s[46:47] offset:3072
	s_branch .LBB0_33
.Lp0_ldB:
	global_load_dwordx4 v[146:149], v191, s[46:47]
	global_load_dwordx4 v[150:153], v191, s[46:47] offset:1024
	global_load_dwordx4 v[154:157], v191, s[46:47] offset:2048
	global_load_dwordx4 v[158:161], v191, s[46:47] offset:3072
